# phase 2: V-block transposition loads issued before the row loop (registers the loop does not use), pack/store after it
# speedup vs baseline: 1.0062x; 1.0062x over previous
.LBB0_183:
	s_cmp_lt_i32 s34, 3
	s_cselect_b64 s[14:15], -1, 0
	s_and_b64 s[6:7], s[14:15], s[6:7]
	s_andn2_b64 vcc, exec, s[6:7]
	v_lshrrev_b32_e32 v130, 6, v0
	s_cbranch_vccnz .LBB0_206
	s_waitcnt lgkmcnt(0)
	s_load_dword s3, s[0:1], 0xd8
	s_lshl_b32 s12, s2, 3
	v_or_b32_e32 v1, s12, v130
	s_movk_i32 s6, 0x2000
	v_cmp_gt_i32_e32 vcc, s6, v1
	s_and_saveexec_b64 s[16:17], vcc
	s_cbranch_execz .LBB0_203
	v_readfirstlane_b32 s85, v130
	s_lshl_b32 s84, s2, 3
	s_nop 0
	s_add_u32 s84, s84, s85
	s_cmp_lt_u32 s84, 0x400
	s_cbranch_scc0 .Lvbp_skip
	v_and_b32_e32 v210, 63, v0
	v_lshlrev_b32_e32 v210, 1, v210
	s_lshr_b32 s86, s84, 9
	s_bfe_u32 s87, s84, 0x70002
	s_and_b32 s90, s84, 3
	s_lshl_b32 s91, s86, 7
	s_add_u32 s91, s91, s87
	s_mul_i32 s91, s91, 0x50000
	s_lshl_b32 s92, s90, 7
	s_add_u32 s91, s91, s92
	s_add_u32 s91, s91, 0x2600
	s_add_u32 s88, s70, s91
	s_addc_u32 s89, s71, 0
	s_add_u32 s88, s88, 0x7900000
	s_addc_u32 s89, s89, 0
	global_load_ushort v211, v210, s[88:89]
	s_add_u32 s88, s88, 0x2800
	s_addc_u32 s89, s89, 0
	global_load_ushort v212, v210, s[88:89]
	s_add_u32 s88, s88, 0x2800
	s_addc_u32 s89, s89, 0
	global_load_ushort v213, v210, s[88:89]
	s_add_u32 s88, s88, 0x2800
	s_addc_u32 s89, s89, 0
	global_load_ushort v214, v210, s[88:89]
	s_add_u32 s88, s88, 0x2800
	s_addc_u32 s89, s89, 0
	global_load_ushort v215, v210, s[88:89]
	s_add_u32 s88, s88, 0x2800
	s_addc_u32 s89, s89, 0
	global_load_ushort v216, v210, s[88:89]
	s_add_u32 s88, s88, 0x2800
	s_addc_u32 s89, s89, 0
	global_load_ushort v217, v210, s[88:89]
	s_add_u32 s88, s88, 0x2800
	s_addc_u32 s89, s89, 0
	global_load_ushort v218, v210, s[88:89]
	s_add_u32 s88, s88, 0x2800
	s_addc_u32 s89, s89, 0
	global_load_ushort v219, v210, s[88:89]
	s_add_u32 s88, s88, 0x2800
	s_addc_u32 s89, s89, 0
	global_load_ushort v220, v210, s[88:89]
	s_add_u32 s88, s88, 0x2800
	s_addc_u32 s89, s89, 0
	global_load_ushort v221, v210, s[88:89]
	s_add_u32 s88, s88, 0x2800
	s_addc_u32 s89, s89, 0
	global_load_ushort v222, v210, s[88:89]
	s_add_u32 s88, s88, 0x2800
	s_addc_u32 s89, s89, 0
	global_load_ushort v223, v210, s[88:89]
	s_add_u32 s88, s88, 0x2800
	s_addc_u32 s89, s89, 0
	global_load_ushort v224, v210, s[88:89]
	s_add_u32 s88, s88, 0x2800
	s_addc_u32 s89, s89, 0
	global_load_ushort v225, v210, s[88:89]
	s_add_u32 s88, s88, 0x2800
	s_addc_u32 s89, s89, 0
	global_load_ushort v226, v210, s[88:89]
	s_add_u32 s88, s88, 0x2800
	s_addc_u32 s89, s89, 0
	global_load_ushort v227, v210, s[88:89]
	s_add_u32 s88, s88, 0x2800
	s_addc_u32 s89, s89, 0
	global_load_ushort v228, v210, s[88:89]
	s_add_u32 s88, s88, 0x2800
	s_addc_u32 s89, s89, 0
	global_load_ushort v229, v210, s[88:89]
	s_add_u32 s88, s88, 0x2800
	s_addc_u32 s89, s89, 0
	global_load_ushort v230, v210, s[88:89]
	s_add_u32 s88, s88, 0x2800
	s_addc_u32 s89, s89, 0
	global_load_ushort v231, v210, s[88:89]
	s_add_u32 s88, s88, 0x2800
	s_addc_u32 s89, s89, 0
	global_load_ushort v232, v210, s[88:89]
	s_add_u32 s88, s88, 0x2800
	s_addc_u32 s89, s89, 0
	global_load_ushort v233, v210, s[88:89]
	s_add_u32 s88, s88, 0x2800
	s_addc_u32 s89, s89, 0
	global_load_ushort v234, v210, s[88:89]
	s_add_u32 s88, s88, 0x2800
	s_addc_u32 s89, s89, 0
	global_load_ushort v235, v210, s[88:89]
	s_add_u32 s88, s88, 0x2800
	s_addc_u32 s89, s89, 0
	global_load_ushort v236, v210, s[88:89]
	s_add_u32 s88, s88, 0x2800
	s_addc_u32 s89, s89, 0
	global_load_ushort v237, v210, s[88:89]
	s_add_u32 s88, s88, 0x2800
	s_addc_u32 s89, s89, 0
	global_load_ushort v238, v210, s[88:89]
	s_add_u32 s88, s88, 0x2800
	s_addc_u32 s89, s89, 0
	global_load_ushort v239, v210, s[88:89]
	s_add_u32 s88, s88, 0x2800
	s_addc_u32 s89, s89, 0
	global_load_ushort v240, v210, s[88:89]
	s_add_u32 s88, s88, 0x2800
	s_addc_u32 s89, s89, 0
	global_load_ushort v241, v210, s[88:89]
	s_add_u32 s88, s88, 0x2800
	s_addc_u32 s89, s89, 0
	global_load_ushort v242, v210, s[88:89]
.Lvbp_skip:
	v_and_b32_e32 v50, 63, v0
	v_lshlrev_b32_e32 v2, 3, v50
	v_and_b32_e32 v6, 0xf8, v2
	global_load_dwordx2 v[48:49], v6, s[64:65]
	v_mbcnt_lo_u32_b32 v4, -1, 0
	global_load_dwordx2 v[6:7], v6, s[66:67]
	v_mbcnt_hi_u32_b32 v51, -1, v4
	v_and_b32_e32 v42, 64, v51
	v_mov_b32_e32 v3, 0
	v_lshlrev_b32_e32 v40, 1, v50
	v_xor_b32_e32 v52, 16, v51
	v_add_u32_e32 v55, 64, v42
	v_lshl_add_u64 v[4:5], s[42:43], 0, v[2:3]
	v_or_b32_e32 v8, 0x1000, v2
	v_or_b32_e32 v10, 0x1200, v2
	v_or_b32_e32 v12, 0x1400, v2
	v_or_b32_e32 v14, 0x1600, v2
	v_or_b32_e32 v16, 0x1800, v2
	v_or_b32_e32 v18, 0x1a00, v2
	v_or_b32_e32 v20, 0x1c00, v2
	v_or_b32_e32 v22, 0x1e00, v2
	v_or_b32_e32 v24, 0x2000, v2
	v_or_b32_e32 v26, 0x2200, v2
	v_or_b32_e32 v28, 0x2400, v2
	v_or_b32_e32 v30, 0x2600, v2
	v_or_b32_e32 v32, 0x2800, v2
	v_or_b32_e32 v34, 0x2a00, v2
	v_or_b32_e32 v36, 0x2c00, v2
	v_or_b32_e32 v38, 0x2e00, v2
	v_or_b32_e32 v53, 0xc00, v40
	v_or_b32_e32 v54, 0xc80, v40
	v_or_b32_e32 v40, 0x3400, v2
	v_or_b32_e32 v2, 0x3600, v2
	v_cmp_lt_i32_e32 vcc, v52, v55
	s_mov_b32 s8, 0x3e000000
	v_lshl_add_u64 v[42:43], s[42:43], 0, v[2:3]
	v_cndmask_b32_e32 v2, v51, v52, vcc
	v_mov_b32_e32 v131, v3
	s_ashr_i32 s13, s12, 31
	s_movk_i32 s19, 0x2800
	v_cmp_gt_u32_e64 s[6:7], 32, v50
	v_lshlrev_b32_e32 v120, 2, v2
	v_lshlrev_b32_e32 v2, 2, v50
	v_lshl_add_u64 v[58:59], v[130:131], 0, s[12:13]
	v_mov_b64_e32 v[50:51], s[70:71]
	v_lshlrev_b32_e32 v44, 2, v53
	v_mad_u64_u32 v[50:51], s[12:13], v58, s19, v[50:51]
	s_movk_i32 s26, 0x1800
	s_mov_b64 s[12:13], 0x3000400
	v_mov_b64_e32 v[56:57], s[68:69]
	s_waitcnt lgkmcnt(0)
	s_lshl_b32 s18, s3, 3
	s_movk_i32 s10, 0xcbf
	v_mov_b32_e32 v9, v3
	v_mov_b32_e32 v11, v3
	v_mov_b32_e32 v13, v3
	v_mov_b32_e32 v15, v3
	v_mov_b32_e32 v17, v3
	v_mov_b32_e32 v19, v3
	v_mov_b32_e32 v21, v3
	v_mov_b32_e32 v23, v3
	v_mov_b32_e32 v25, v3
	v_mov_b32_e32 v27, v3
	v_mov_b32_e32 v29, v3
	v_mov_b32_e32 v31, v3
	v_mov_b32_e32 v33, v3
	v_mov_b32_e32 v35, v3
	v_mov_b32_e32 v37, v3
	v_mov_b32_e32 v39, v3
	v_mov_b32_e32 v45, v3
	v_mov_b32_e32 v47, v3
	v_mov_b32_e32 v41, v3
	v_lshlrev_b32_e32 v46, 2, v54
	v_cmp_lt_u32_e64 s[10:11], s10, v54
	v_mad_i32_i24 v51, v59, s19, v51
	s_ashr_i32 s19, s18, 31
	v_lshlrev_b64 v[54:55], 9, v[58:59]
	s_movk_i32 s47, 0x1000
	v_lshl_add_u64 v[8:9], s[42:43], 0, v[8:9]
	v_lshl_add_u64 v[10:11], s[42:43], 0, v[10:11]
	v_lshl_add_u64 v[12:13], s[42:43], 0, v[12:13]
	v_lshl_add_u64 v[14:15], s[42:43], 0, v[14:15]
	v_lshl_add_u64 v[16:17], s[42:43], 0, v[16:17]
	s_waitcnt vmcnt(1)
	v_pk_mul_f32 v[48:49], v[48:49], s[8:9] op_sel_hi:[1,0]
	s_movk_i32 s8, 0xc5f
	v_cmp_lt_u32_e64 s[8:9], s8, v53
	v_lshlrev_b64 v[52:53], 11, v[58:59]
	v_lshl_add_u64 v[52:53], s[68:69], 0, v[52:53]
	v_lshl_add_u64 v[52:53], v[52:53], 0, s[12:13]
	v_mad_u64_u32 v[56:57], s[12:13], v58, s26, v[56:57]
	v_mad_i32_i24 v57, v59, s26, v57
	v_lshlrev_b64 v[58:59], 10, v[58:59]
	v_lshl_add_u64 v[18:19], s[42:43], 0, v[18:19]
	v_lshl_add_u64 v[20:21], s[42:43], 0, v[20:21]
	v_lshl_add_u64 v[22:23], s[42:43], 0, v[22:23]
	v_lshl_add_u64 v[24:25], s[42:43], 0, v[24:25]
	v_lshl_add_u64 v[26:27], s[42:43], 0, v[26:27]
	v_lshl_add_u64 v[28:29], s[42:43], 0, v[28:29]
	v_lshl_add_u64 v[30:31], s[42:43], 0, v[30:31]
	v_lshl_add_u64 v[32:33], s[42:43], 0, v[32:33]
	v_lshl_add_u64 v[34:35], s[42:43], 0, v[34:35]
	v_lshl_add_u64 v[36:37], s[42:43], 0, v[36:37]
	v_lshl_add_u64 v[38:39], s[42:43], 0, v[38:39]
	v_lshl_add_u64 v[40:41], s[42:43], 0, v[40:41]
	v_lshl_add_u64 v[44:45], s[42:43], 0, v[44:45]
	v_lshl_add_u64 v[46:47], s[42:43], 0, v[46:47]
	s_mul_i32 s20, s3, 0x14000
	s_mul_hi_i32 s21, s18, 0x2800
	s_lshl_b64 s[22:23], s[18:19], 11
	v_lshl_add_u64 v[54:55], s[70:71], 0, v[54:55]
	s_lshl_b64 s[24:25], s[18:19], 9
	s_mul_i32 s26, s3, 0xc000
	s_mul_hi_i32 s27, s18, 0x1800
	v_lshl_add_u64 v[58:59], s[70:71], 0, v[58:59]
	s_lshl_b64 s[28:29], s[18:19], 10
	s_mov_b64 s[30:31], 0
	s_mov_b32 s19, 0x7901000
	s_mov_b32 s43, 0x3f200000
	s_mov_b32 s64, 0x3fb8aa3b
	s_mov_b32 s65, 0xc2ce8ed0
	s_mov_b32 s66, 0x42b17218
	v_mov_b32_e32 v121, 0x3ca908c9
	s_brev_b32 s67, -2
	s_mov_b32 s42, 0x3c800000
	s_mov_b32 s46, 0x358637bd
	s_mov_b32 s72, 0x800000
	s_mov_b32 s73, 0x13100000
	s_movk_i32 s74, 0x1fff
	v_mov_b32_e32 v122, 0xffffd800
	v_mov_b32_e32 v123, 0x7f800000
	s_branch .LBB0_187

.Lvb_loop:
	s_lshr_b32 s9, s8, 9
	s_bfe_u32 s10, s8, 0x70002
	s_and_b32 s11, s8, 3
	s_lshl_b32 s12, s9, 2
	s_add_u32 s12, s12, s11
	s_lshl_b32 s12, s12, 7
	s_add_u32 s12, s12, s10
	s_lshl_b32 s12, s12, 12
	s_add_u32 s18, s70, s12
	s_addc_u32 s19, s71, 0
	s_add_u32 s18, s18, 0x13500000
	s_addc_u32 s19, s19, 0
	s_waitcnt vmcnt(0)
	v_lshl_or_b32 v50, v212, 16, v211
	v_lshl_or_b32 v51, v214, 16, v213
	v_lshl_or_b32 v52, v228, 16, v227
	v_lshl_or_b32 v53, v230, 16, v229
	v_lshl_or_b32 v54, v216, 16, v215
	v_lshl_or_b32 v55, v218, 16, v217
	v_lshl_or_b32 v56, v232, 16, v231
	v_lshl_or_b32 v57, v234, 16, v233
	v_lshl_or_b32 v58, v220, 16, v219
	v_lshl_or_b32 v59, v222, 16, v221
	v_lshl_or_b32 v60, v236, 16, v235
	v_lshl_or_b32 v61, v238, 16, v237
	v_lshl_or_b32 v62, v224, 16, v223
	v_lshl_or_b32 v63, v226, 16, v225
	v_lshl_or_b32 v64, v240, 16, v239
	v_lshl_or_b32 v65, v242, 16, v241
	global_store_dwordx4 v3, v[50:53], s[18:19]
	global_store_dwordx4 v3, v[54:57], s[18:19] offset:16
	global_store_dwordx4 v3, v[58:61], s[18:19] offset:32
	global_store_dwordx4 v3, v[62:65], s[18:19] offset:48

.Lat_pv_done:
	s_nop 7
	v_cvt_pk_bf16_f32 v22, v240, v240
	v_cvt_pk_bf16_f32 v23, v241, v241
	v_cvt_pk_bf16_f32 v24, v242, v242
	v_cvt_pk_bf16_f32 v25, v243, v243
	v_cvt_pk_bf16_f32 v26, v244, v244
	v_cvt_pk_bf16_f32 v27, v245, v245
	v_cvt_pk_bf16_f32 v28, v246, v246
	v_cvt_pk_bf16_f32 v29, v247, v247
	v_cvt_pk_bf16_f32 v134, v248, v248
	v_cvt_pk_bf16_f32 v135, v249, v249
	v_cvt_pk_bf16_f32 v136, v250, v250
	v_cvt_pk_bf16_f32 v137, v251, v251
	v_cvt_pk_bf16_f32 v138, v120, v120
	v_cvt_pk_bf16_f32 v139, v121, v121
	v_cvt_pk_bf16_f32 v150, v122, v122
	v_cvt_pk_bf16_f32 v151, v123, v123
	global_store_short v17, v22, s[20:21]
	global_store_short v17, v23, s[20:21] offset:2048
	global_store_short v18, v24, s[20:21]
	global_store_short v18, v25, s[20:21] offset:2048
	global_store_short v17, v26, s[20:21] offset:32
	global_store_short v17, v27, s[20:21] offset:2080
	global_store_short v18, v28, s[20:21] offset:32
	global_store_short v18, v29, s[20:21] offset:2080
	global_store_short v17, v134, s[20:21] offset:64
	global_store_short v17, v135, s[20:21] offset:2112
	global_store_short v18, v136, s[20:21] offset:64
	global_store_short v18, v137, s[20:21] offset:2112
	global_store_short v17, v138, s[20:21] offset:96
	global_store_short v17, v139, s[20:21] offset:2144
	global_store_short v18, v150, s[20:21] offset:96
	global_store_short v18, v151, s[20:21] offset:2144
	s_add_u32 s3, s3, s6
	s_cmp_lt_u32 s3, 0x2000
	s_cbranch_scc1 .Lat_loop
	v_and_b32_e32 v10, 15, v0
	s_add_u32 s74, s0, 0xd8
	s_addc_u32 s75, s1, 0
	v_mov_b64_e32 v[2:3], s[74:75]
	s_mov_b64 s[64:65], exec
	s_nop 0
	s_nop 0
	s_nop 0
	s_nop 0
	s_nop 0
	s_nop 0
	s_nop 0
	s_nop 0
	s_nop 0
	s_nop 0
	s_nop 0
	s_nop 0
	s_nop 0
	s_nop 0
	s_nop 0
	s_nop 0
	s_nop 0
	s_nop 0
	s_nop 0
	s_nop 0
	s_nop 0
	s_nop 0
	s_nop 0
	s_nop 0
	s_nop 0
	s_nop 0
	s_nop 0
	s_nop 0
	s_nop 0
	s_nop 0
	s_nop 0
	s_nop 0
	s_nop 0
	s_nop 0
	s_nop 0
	s_nop 0
